# prep loops: boundary-row loads without exec==0 branches, one alignment nop before loop (a)
# speedup vs baseline: 1.0020x; 1.0006x over previous
.LBB0_313:
	s_or_b64 exec, exec, s[0:1]
	v_readlane_b32 s2, v251, 16
	v_readlane_b32 s3, v251, 17
	s_waitcnt vmcnt(0) lgkmcnt(0)
	s_barrier
	s_load_dword s0, s[2:3], 0x10
	s_nop 0
	s_load_dword s2, s[2:3], 0x0
	s_waitcnt lgkmcnt(0)
	s_lshr_b32 s0, s0, 16
	s_cmp_lg_u32 s0, 0
	s_cselect_b64 s[0:1], -1, 0
	s_cmp_lg_u64 s[0:1], 0
	v_readlane_b32 s0, v251, 27
	s_addc_u32 s28, s2, 0
	s_lshl_b32 s34, s28, 9
	v_add_u32_e32 v58, s0, v59
	s_mov_b32 s0, 0x110000
	v_cmp_gt_i32_e32 vcc, s0, v58
	s_and_saveexec_b64 s[38:39], vcc
	s_cbranch_execz .LBB0_384
	v_readlane_b32 s0, v253, 24
	s_lshl_b32 s26, s28, 13
	s_mov_b64 s[6:7], 0
	v_lshl_add_u32 v76, v59, 3, s0
	v_mov_b32_e32 v74, v76
	v_mov_b32_e32 v39, v58
	v_and_b32_e32 v116, 0xf8, v76
	v_lshlrev_b32_e32 v116, 2, v116
	v_readlane_b32 s2, v254, 48
	v_readlane_b32 s3, v254, 49
	s_nop 4
	global_load_dwordx4 v[84:87], v116, s[2:3]
	global_load_dwordx4 v[88:91], v116, s[2:3] offset:16
	global_load_dwordx4 v[92:95], v116, s[2:3] offset:1024
	global_load_dwordx4 v[96:99], v116, s[2:3] offset:1040
	global_load_dwordx4 v[108:111], v116, s[2:3] offset:2048
	global_load_dwordx4 v[112:115], v116, s[2:3] offset:2064
	s_waitcnt vmcnt(0)
	s_nop 0
	s_branch .LBB0_317
